# hand-written out-proj GEMM loop: fragment ping-pong, 1 barrier per k-step, next-tile prefetch
# speedup vs baseline: 1.0042x; 1.0042x over previous
.LBB0_1110:
	s_or_b64 exec, exec, s[0:1]
	v_readlane_b32 s0, v252, 21
	v_readlane_b32 s1, v252, 22
	v_mov_b32_e32 v4, v222
	s_andn2_b64 vcc, exec, s[0:1]
	s_waitcnt lgkmcnt(0)
	s_barrier
	s_cbranch_vccnz .LBB0_1121
	v_lshrrev_b32_e32 v0, 3, v222
	v_xor_b32_e32 v1, v0, v222
	v_and_b32_e32 v1, 7, v1
	v_lshlrev_b32_e32 v1, 4, v1
	v_lshl_add_u32 v164, v0, 7, v1
	v_add_u32_e32 v164, 32, v164
	v_and_b32_e32 v1, 7, v222
	v_lshlrev_b32_e32 v1, 4, v1
	v_lshl_or_b32 v169, v0, 11, v1
	v_add_u32_e32 v170, 0x10000, v169
	v_add_u32_e32 v171, 0x20000, v169
	v_add_u32_e32 v172, 0x30000, v169
	v_bfe_u32 v0, v222, 4, 2
	v_and_b32_e32 v1, 7, v222
	v_xor_b32_e32 v1, v0, v1
	v_lshlrev_b32_e32 v1, 4, v1
	v_and_b32_e32 v2, 15, v222
	v_xor_b32_e32 v167, 64, v1
	v_lshl_add_u32 v1, v2, 7, v1
	v_lshl_add_u32 v167, v2, 7, v167
	v_add_u32_e32 v1, 32, v1
	v_add_u32_e32 v167, 32, v167
	v_bfe_u32 v165, v222, 6, 1
	v_bfe_u32 v166, v222, 7, 1
	v_lshl_add_u32 v168, v166, 13, v167
	v_lshl_add_u32 v167, v165, 13, v167
	v_lshl_add_u32 v165, v165, 13, v1
	v_lshl_add_u32 v166, v166, 13, v1
	v_bfe_u32 v1, v222, 7, 1
	v_lshl_add_u32 v1, v1, 6, v2
	v_mul_u32_u24_e32 v1, 0x110, v1
	v_lshl_add_u32 v1, v0, 3, v1
	v_bfe_u32 v2, v222, 6, 1
	v_lshl_add_u32 v1, v2, 7, v1
	v_add_u32_e32 v173, 32, v1
	v_lshrrev_b32_e32 v0, 4, v222
	v_and_b32_e32 v1, 15, v222
	v_lshlrev_b32_e32 v1, 4, v1
	v_lshl_or_b32 v175, v0, 11, v1
	v_mul_u32_u24_e32 v0, 0x110, v0
	v_add3_u32 v174, v0, v1, 32
	v_readlane_b32 s8, v252, 19
	v_readlane_b32 s9, v252, 20
	s_lshl_b32 s0, s16, 21
	s_add_u32 s8, s8, s0
	s_addc_u32 s9, s9, 0
	v_readlane_b32 s10, v252, 3
	v_readlane_b32 s11, v252, 8
	v_readlane_b32 s13, v252, 0
	s_cmp_lt_u32 s10, 272
	s_cbranch_scc0 .Lg1_done
	s_and_b32 s12, s10, 7
	s_lshr_b32 s22, s10, 3
	s_add_i32 s22, s22, s11
	s_lshl_b32 s12, s12, 18
	s_lshl_b32 s22, s22, 18
	s_add_u32 s0, s8, s12
	s_addc_u32 s1, s9, 0
	s_add_u32 s4, s20, s22
	s_addc_u32 s5, s21, 0
	global_load_dwordx4 v[68:71], v169, s[0:1]
	global_load_dwordx4 v[84:87], v169, s[4:5]
	global_load_dwordx4 v[72:75], v170, s[0:1]
	global_load_dwordx4 v[88:91], v170, s[4:5]
	global_load_dwordx4 v[76:79], v171, s[0:1]
	global_load_dwordx4 v[92:95], v171, s[4:5]
	global_load_dwordx4 v[80:83], v172, s[0:1]
	global_load_dwordx4 v[96:99], v172, s[4:5]
	global_load_dwordx4 v[100:103], v169, s[0:1] offset:128
	global_load_dwordx4 v[116:119], v169, s[4:5] offset:128
	global_load_dwordx4 v[104:107], v170, s[0:1] offset:128
	global_load_dwordx4 v[120:123], v170, s[4:5] offset:128
	global_load_dwordx4 v[108:111], v171, s[0:1] offset:128
	global_load_dwordx4 v[124:127], v171, s[4:5] offset:128
	global_load_dwordx4 v[112:115], v172, s[0:1] offset:128
	global_load_dwordx4 v[128:131], v172, s[4:5] offset:128
	s_waitcnt vmcnt(8)
	s_branch .Lg1_pro
.Lg1_again:
	s_waitcnt vmcnt(16)
.Lg1_pro:
	ds_write_b128 v164, v[68:71]
	ds_write_b128 v164, v[84:87] offset:32768
	ds_write_b128 v164, v[72:75] offset:4096
	ds_write_b128 v164, v[88:91] offset:36864
	ds_write_b128 v164, v[76:79] offset:8192
	ds_write_b128 v164, v[92:95] offset:40960
	ds_write_b128 v164, v[80:83] offset:12288
	ds_write_b128 v164, v[96:99] offset:45056
	global_load_dwordx4 v[68:71], v169, s[0:1] offset:256
	global_load_dwordx4 v[84:87], v169, s[4:5] offset:256
	global_load_dwordx4 v[72:75], v170, s[0:1] offset:256
	global_load_dwordx4 v[88:91], v170, s[4:5] offset:256
	global_load_dwordx4 v[76:79], v171, s[0:1] offset:256
	global_load_dwordx4 v[92:95], v171, s[4:5] offset:256
	global_load_dwordx4 v[80:83], v172, s[0:1] offset:256
	global_load_dwordx4 v[96:99], v172, s[4:5] offset:256
	s_and_b32 s12, s10, 7
	s_lshr_b32 s22, s10, 3
	s_add_i32 s22, s22, s11
	s_lshl_b32 s12, s12, 8
	s_lshl_b32 s22, s22, 18
	s_add_u32 s6, s24, s22
	s_addc_u32 s7, s25, 0
	s_add_u32 s6, s6, s12
	s_addc_u32 s7, s7, 0
	s_waitcnt lgkmcnt(0)
	s_barrier
	ds_read_b128 v[132:135], v165
	ds_read_b128 v[148:151], v166 offset:32768
	ds_read_b128 v[136:139], v165 offset:2048
	ds_read_b128 v[152:155], v166 offset:34816
	ds_read_b128 v[140:143], v165 offset:4096
	ds_read_b128 v[156:159], v166 offset:36864
	ds_read_b128 v[144:147], v165 offset:6144
	ds_read_b128 v[160:163], v166 offset:38912
	s_waitcnt lgkmcnt(0)
	v_mfma_f32_16x16x32_bf16 v[4:7], v[132:135], v[148:151], 0
	ds_read_b128 v[178:181], v167
	s_waitcnt vmcnt(8)
	ds_write_b128 v164, v[100:103] offset:16384
	v_mfma_f32_16x16x32_bf16 v[8:11], v[132:135], v[152:155], 0
	ds_read_b128 v[194:197], v168 offset:32768
	ds_write_b128 v164, v[116:119] offset:49152
	v_mfma_f32_16x16x32_bf16 v[12:15], v[132:135], v[156:159], 0
	ds_read_b128 v[182:185], v167 offset:2048
	ds_write_b128 v164, v[104:107] offset:20480
	v_mfma_f32_16x16x32_bf16 v[16:19], v[132:135], v[160:163], 0
	ds_read_b128 v[198:201], v168 offset:34816
	ds_write_b128 v164, v[120:123] offset:53248
	v_mfma_f32_16x16x32_bf16 v[20:23], v[136:139], v[148:151], 0
	ds_read_b128 v[186:189], v167 offset:4096
	ds_write_b128 v164, v[108:111] offset:24576
	v_mfma_f32_16x16x32_bf16 v[24:27], v[136:139], v[152:155], 0
	ds_read_b128 v[202:205], v168 offset:36864
	ds_write_b128 v164, v[124:127] offset:57344
	v_mfma_f32_16x16x32_bf16 v[28:31], v[136:139], v[156:159], 0
	ds_read_b128 v[190:193], v167 offset:6144
	ds_write_b128 v164, v[112:115] offset:28672
	v_mfma_f32_16x16x32_bf16 v[32:35], v[136:139], v[160:163], 0
	ds_read_b128 v[206:209], v168 offset:38912
	ds_write_b128 v164, v[128:131] offset:61440
	v_mfma_f32_16x16x32_bf16 v[36:39], v[140:143], v[148:151], 0
	global_load_dwordx4 v[100:103], v169, s[0:1] offset:384
	v_mfma_f32_16x16x32_bf16 v[40:43], v[140:143], v[152:155], 0
	global_load_dwordx4 v[116:119], v169, s[4:5] offset:384
	v_mfma_f32_16x16x32_bf16 v[44:47], v[140:143], v[156:159], 0
	global_load_dwordx4 v[104:107], v170, s[0:1] offset:384
	v_mfma_f32_16x16x32_bf16 v[48:51], v[140:143], v[160:163], 0
	global_load_dwordx4 v[120:123], v170, s[4:5] offset:384
	v_mfma_f32_16x16x32_bf16 v[52:55], v[144:147], v[148:151], 0
	global_load_dwordx4 v[108:111], v171, s[0:1] offset:384
	v_mfma_f32_16x16x32_bf16 v[56:59], v[144:147], v[152:155], 0
	global_load_dwordx4 v[124:127], v171, s[4:5] offset:384
	v_mfma_f32_16x16x32_bf16 v[60:63], v[144:147], v[156:159], 0
	global_load_dwordx4 v[112:115], v172, s[0:1] offset:384
	v_mfma_f32_16x16x32_bf16 v[64:67], v[144:147], v[160:163], 0
	global_load_dwordx4 v[128:131], v172, s[4:5] offset:384
	s_waitcnt lgkmcnt(0)
	s_barrier
	v_mfma_f32_16x16x32_bf16 v[4:7], v[178:181], v[194:197], v[4:7]
	ds_read_b128 v[132:135], v165 offset:16384
	v_mfma_f32_16x16x32_bf16 v[8:11], v[178:181], v[198:201], v[8:11]
	ds_read_b128 v[148:151], v166 offset:49152
	v_mfma_f32_16x16x32_bf16 v[12:15], v[178:181], v[202:205], v[12:15]
	ds_read_b128 v[136:139], v165 offset:18432
	v_mfma_f32_16x16x32_bf16 v[16:19], v[178:181], v[206:209], v[16:19]
	ds_read_b128 v[152:155], v166 offset:51200
	v_mfma_f32_16x16x32_bf16 v[20:23], v[182:185], v[194:197], v[20:23]
	ds_read_b128 v[140:143], v165 offset:20480
	v_mfma_f32_16x16x32_bf16 v[24:27], v[182:185], v[198:201], v[24:27]
	ds_read_b128 v[156:159], v166 offset:53248
	v_mfma_f32_16x16x32_bf16 v[28:31], v[182:185], v[202:205], v[28:31]
	ds_read_b128 v[144:147], v165 offset:22528
	v_mfma_f32_16x16x32_bf16 v[32:35], v[182:185], v[206:209], v[32:35]
	ds_read_b128 v[160:163], v166 offset:55296
	v_mfma_f32_16x16x32_bf16 v[36:39], v[186:189], v[194:197], v[36:39]
	v_mfma_f32_16x16x32_bf16 v[40:43], v[186:189], v[198:201], v[40:43]
	v_mfma_f32_16x16x32_bf16 v[44:47], v[186:189], v[202:205], v[44:47]
	v_mfma_f32_16x16x32_bf16 v[48:51], v[186:189], v[206:209], v[48:51]
	v_mfma_f32_16x16x32_bf16 v[52:55], v[190:193], v[194:197], v[52:55]
	v_mfma_f32_16x16x32_bf16 v[56:59], v[190:193], v[198:201], v[56:59]
	v_mfma_f32_16x16x32_bf16 v[60:63], v[190:193], v[202:205], v[60:63]
	v_mfma_f32_16x16x32_bf16 v[64:67], v[190:193], v[206:209], v[64:67]
	s_waitcnt lgkmcnt(0)
	v_mfma_f32_16x16x32_bf16 v[4:7], v[132:135], v[148:151], v[4:7]
	ds_read_b128 v[178:181], v167 offset:16384
	s_waitcnt vmcnt(8)
	ds_write_b128 v164, v[68:71]
	v_mfma_f32_16x16x32_bf16 v[8:11], v[132:135], v[152:155], v[8:11]
	ds_read_b128 v[194:197], v168 offset:49152
	ds_write_b128 v164, v[84:87] offset:32768
	v_mfma_f32_16x16x32_bf16 v[12:15], v[132:135], v[156:159], v[12:15]
	ds_read_b128 v[182:185], v167 offset:18432
	ds_write_b128 v164, v[72:75] offset:4096
	v_mfma_f32_16x16x32_bf16 v[16:19], v[132:135], v[160:163], v[16:19]
	ds_read_b128 v[198:201], v168 offset:51200
	ds_write_b128 v164, v[88:91] offset:36864
	v_mfma_f32_16x16x32_bf16 v[20:23], v[136:139], v[148:151], v[20:23]
	ds_read_b128 v[186:189], v167 offset:20480
	ds_write_b128 v164, v[76:79] offset:8192
	v_mfma_f32_16x16x32_bf16 v[24:27], v[136:139], v[152:155], v[24:27]
	ds_read_b128 v[202:205], v168 offset:53248
	ds_write_b128 v164, v[92:95] offset:40960
	v_mfma_f32_16x16x32_bf16 v[28:31], v[136:139], v[156:159], v[28:31]
	ds_read_b128 v[190:193], v167 offset:22528
	ds_write_b128 v164, v[80:83] offset:12288
	v_mfma_f32_16x16x32_bf16 v[32:35], v[136:139], v[160:163], v[32:35]
	ds_read_b128 v[206:209], v168 offset:55296
	ds_write_b128 v164, v[96:99] offset:45056
	v_mfma_f32_16x16x32_bf16 v[36:39], v[140:143], v[148:151], v[36:39]
	global_load_dwordx4 v[68:71], v169, s[0:1] offset:512
	v_mfma_f32_16x16x32_bf16 v[40:43], v[140:143], v[152:155], v[40:43]
	global_load_dwordx4 v[84:87], v169, s[4:5] offset:512
	v_mfma_f32_16x16x32_bf16 v[44:47], v[140:143], v[156:159], v[44:47]
	global_load_dwordx4 v[72:75], v170, s[0:1] offset:512
	v_mfma_f32_16x16x32_bf16 v[48:51], v[140:143], v[160:163], v[48:51]
	global_load_dwordx4 v[88:91], v170, s[4:5] offset:512
	v_mfma_f32_16x16x32_bf16 v[52:55], v[144:147], v[148:151], v[52:55]
	global_load_dwordx4 v[76:79], v171, s[0:1] offset:512
	v_mfma_f32_16x16x32_bf16 v[56:59], v[144:147], v[152:155], v[56:59]
	global_load_dwordx4 v[92:95], v171, s[4:5] offset:512
	v_mfma_f32_16x16x32_bf16 v[60:63], v[144:147], v[156:159], v[60:63]
	global_load_dwordx4 v[80:83], v172, s[0:1] offset:512
	v_mfma_f32_16x16x32_bf16 v[64:67], v[144:147], v[160:163], v[64:67]
	global_load_dwordx4 v[96:99], v172, s[4:5] offset:512
	s_waitcnt lgkmcnt(0)
	s_barrier
	v_mfma_f32_16x16x32_bf16 v[4:7], v[178:181], v[194:197], v[4:7]
	ds_read_b128 v[132:135], v165
	v_mfma_f32_16x16x32_bf16 v[8:11], v[178:181], v[198:201], v[8:11]
	ds_read_b128 v[148:151], v166 offset:32768
	v_mfma_f32_16x16x32_bf16 v[12:15], v[178:181], v[202:205], v[12:15]
	ds_read_b128 v[136:139], v165 offset:2048
	v_mfma_f32_16x16x32_bf16 v[16:19], v[178:181], v[206:209], v[16:19]
	ds_read_b128 v[152:155], v166 offset:34816
	v_mfma_f32_16x16x32_bf16 v[20:23], v[182:185], v[194:197], v[20:23]
	ds_read_b128 v[140:143], v165 offset:4096
	v_mfma_f32_16x16x32_bf16 v[24:27], v[182:185], v[198:201], v[24:27]
	ds_read_b128 v[156:159], v166 offset:36864
	v_mfma_f32_16x16x32_bf16 v[28:31], v[182:185], v[202:205], v[28:31]
	ds_read_b128 v[144:147], v165 offset:6144
	v_mfma_f32_16x16x32_bf16 v[32:35], v[182:185], v[206:209], v[32:35]
	ds_read_b128 v[160:163], v166 offset:38912
	v_mfma_f32_16x16x32_bf16 v[36:39], v[186:189], v[194:197], v[36:39]
	v_mfma_f32_16x16x32_bf16 v[40:43], v[186:189], v[198:201], v[40:43]
	v_mfma_f32_16x16x32_bf16 v[44:47], v[186:189], v[202:205], v[44:47]
	v_mfma_f32_16x16x32_bf16 v[48:51], v[186:189], v[206:209], v[48:51]
	v_mfma_f32_16x16x32_bf16 v[52:55], v[190:193], v[194:197], v[52:55]
	v_mfma_f32_16x16x32_bf16 v[56:59], v[190:193], v[198:201], v[56:59]
	v_mfma_f32_16x16x32_bf16 v[60:63], v[190:193], v[202:205], v[60:63]
	v_mfma_f32_16x16x32_bf16 v[64:67], v[190:193], v[206:209], v[64:67]
	s_waitcnt lgkmcnt(0)
	v_mfma_f32_16x16x32_bf16 v[4:7], v[132:135], v[148:151], v[4:7]
	ds_read_b128 v[178:181], v167
	s_waitcnt vmcnt(8)
	ds_write_b128 v164, v[100:103] offset:16384
	v_mfma_f32_16x16x32_bf16 v[8:11], v[132:135], v[152:155], v[8:11]
	ds_read_b128 v[194:197], v168 offset:32768
	ds_write_b128 v164, v[116:119] offset:49152
	v_mfma_f32_16x16x32_bf16 v[12:15], v[132:135], v[156:159], v[12:15]
	ds_read_b128 v[182:185], v167 offset:2048
	ds_write_b128 v164, v[104:107] offset:20480
	v_mfma_f32_16x16x32_bf16 v[16:19], v[132:135], v[160:163], v[16:19]
	ds_read_b128 v[198:201], v168 offset:34816
	ds_write_b128 v164, v[120:123] offset:53248
	v_mfma_f32_16x16x32_bf16 v[20:23], v[136:139], v[148:151], v[20:23]
	ds_read_b128 v[186:189], v167 offset:4096
	ds_write_b128 v164, v[108:111] offset:24576
	v_mfma_f32_16x16x32_bf16 v[24:27], v[136:139], v[152:155], v[24:27]
	ds_read_b128 v[202:205], v168 offset:36864
	ds_write_b128 v164, v[124:127] offset:57344
	v_mfma_f32_16x16x32_bf16 v[28:31], v[136:139], v[156:159], v[28:31]
	ds_read_b128 v[190:193], v167 offset:6144
	ds_write_b128 v164, v[112:115] offset:28672
	v_mfma_f32_16x16x32_bf16 v[32:35], v[136:139], v[160:163], v[32:35]
	ds_read_b128 v[206:209], v168 offset:38912
	ds_write_b128 v164, v[128:131] offset:61440
	v_mfma_f32_16x16x32_bf16 v[36:39], v[140:143], v[148:151], v[36:39]
	global_load_dwordx4 v[100:103], v169, s[0:1] offset:640
	v_mfma_f32_16x16x32_bf16 v[40:43], v[140:143], v[152:155], v[40:43]
	global_load_dwordx4 v[116:119], v169, s[4:5] offset:640
	v_mfma_f32_16x16x32_bf16 v[44:47], v[140:143], v[156:159], v[44:47]
	global_load_dwordx4 v[104:107], v170, s[0:1] offset:640
	v_mfma_f32_16x16x32_bf16 v[48:51], v[140:143], v[160:163], v[48:51]
	global_load_dwordx4 v[120:123], v170, s[4:5] offset:640
	v_mfma_f32_16x16x32_bf16 v[52:55], v[144:147], v[148:151], v[52:55]
	global_load_dwordx4 v[108:111], v171, s[0:1] offset:640
	v_mfma_f32_16x16x32_bf16 v[56:59], v[144:147], v[152:155], v[56:59]
	global_load_dwordx4 v[124:127], v171, s[4:5] offset:640
	v_mfma_f32_16x16x32_bf16 v[60:63], v[144:147], v[156:159], v[60:63]
	global_load_dwordx4 v[112:115], v172, s[0:1] offset:640
	v_mfma_f32_16x16x32_bf16 v[64:67], v[144:147], v[160:163], v[64:67]
	global_load_dwordx4 v[128:131], v172, s[4:5] offset:640
	s_waitcnt lgkmcnt(0)
	s_barrier
	v_mfma_f32_16x16x32_bf16 v[4:7], v[178:181], v[194:197], v[4:7]
	ds_read_b128 v[132:135], v165 offset:16384
	v_mfma_f32_16x16x32_bf16 v[8:11], v[178:181], v[198:201], v[8:11]
	ds_read_b128 v[148:151], v166 offset:49152
	v_mfma_f32_16x16x32_bf16 v[12:15], v[178:181], v[202:205], v[12:15]
	ds_read_b128 v[136:139], v165 offset:18432
	v_mfma_f32_16x16x32_bf16 v[16:19], v[178:181], v[206:209], v[16:19]
	ds_read_b128 v[152:155], v166 offset:51200
	v_mfma_f32_16x16x32_bf16 v[20:23], v[182:185], v[194:197], v[20:23]
	ds_read_b128 v[140:143], v165 offset:20480
	v_mfma_f32_16x16x32_bf16 v[24:27], v[182:185], v[198:201], v[24:27]
	ds_read_b128 v[156:159], v166 offset:53248
	v_mfma_f32_16x16x32_bf16 v[28:31], v[182:185], v[202:205], v[28:31]
	ds_read_b128 v[144:147], v165 offset:22528
	v_mfma_f32_16x16x32_bf16 v[32:35], v[182:185], v[206:209], v[32:35]
	ds_read_b128 v[160:163], v166 offset:55296
	v_mfma_f32_16x16x32_bf16 v[36:39], v[186:189], v[194:197], v[36:39]
	v_mfma_f32_16x16x32_bf16 v[40:43], v[186:189], v[198:201], v[40:43]
	v_mfma_f32_16x16x32_bf16 v[44:47], v[186:189], v[202:205], v[44:47]
	v_mfma_f32_16x16x32_bf16 v[48:51], v[186:189], v[206:209], v[48:51]
	v_mfma_f32_16x16x32_bf16 v[52:55], v[190:193], v[194:197], v[52:55]
	v_mfma_f32_16x16x32_bf16 v[56:59], v[190:193], v[198:201], v[56:59]
	v_mfma_f32_16x16x32_bf16 v[60:63], v[190:193], v[202:205], v[60:63]
	v_mfma_f32_16x16x32_bf16 v[64:67], v[190:193], v[206:209], v[64:67]
	s_waitcnt lgkmcnt(0)
	v_mfma_f32_16x16x32_bf16 v[4:7], v[132:135], v[148:151], v[4:7]
	ds_read_b128 v[178:181], v167 offset:16384
	s_waitcnt vmcnt(8)
	ds_write_b128 v164, v[68:71]
	v_mfma_f32_16x16x32_bf16 v[8:11], v[132:135], v[152:155], v[8:11]
	ds_read_b128 v[194:197], v168 offset:49152
	ds_write_b128 v164, v[84:87] offset:32768
	v_mfma_f32_16x16x32_bf16 v[12:15], v[132:135], v[156:159], v[12:15]
	ds_read_b128 v[182:185], v167 offset:18432
	ds_write_b128 v164, v[72:75] offset:4096
	v_mfma_f32_16x16x32_bf16 v[16:19], v[132:135], v[160:163], v[16:19]
	ds_read_b128 v[198:201], v168 offset:51200
	ds_write_b128 v164, v[88:91] offset:36864
	v_mfma_f32_16x16x32_bf16 v[20:23], v[136:139], v[148:151], v[20:23]
	ds_read_b128 v[186:189], v167 offset:20480
	ds_write_b128 v164, v[76:79] offset:8192
	v_mfma_f32_16x16x32_bf16 v[24:27], v[136:139], v[152:155], v[24:27]
	ds_read_b128 v[202:205], v168 offset:53248
	ds_write_b128 v164, v[92:95] offset:40960
	v_mfma_f32_16x16x32_bf16 v[28:31], v[136:139], v[156:159], v[28:31]
	ds_read_b128 v[190:193], v167 offset:22528
	ds_write_b128 v164, v[80:83] offset:12288
	v_mfma_f32_16x16x32_bf16 v[32:35], v[136:139], v[160:163], v[32:35]
	ds_read_b128 v[206:209], v168 offset:55296
	ds_write_b128 v164, v[96:99] offset:45056
	v_mfma_f32_16x16x32_bf16 v[36:39], v[140:143], v[148:151], v[36:39]
	global_load_dwordx4 v[68:71], v169, s[0:1] offset:768
	v_mfma_f32_16x16x32_bf16 v[40:43], v[140:143], v[152:155], v[40:43]
	global_load_dwordx4 v[84:87], v169, s[4:5] offset:768
	v_mfma_f32_16x16x32_bf16 v[44:47], v[140:143], v[156:159], v[44:47]
	global_load_dwordx4 v[72:75], v170, s[0:1] offset:768
	v_mfma_f32_16x16x32_bf16 v[48:51], v[140:143], v[160:163], v[48:51]
	global_load_dwordx4 v[88:91], v170, s[4:5] offset:768
	v_mfma_f32_16x16x32_bf16 v[52:55], v[144:147], v[148:151], v[52:55]
	global_load_dwordx4 v[76:79], v171, s[0:1] offset:768
	v_mfma_f32_16x16x32_bf16 v[56:59], v[144:147], v[152:155], v[56:59]
	global_load_dwordx4 v[92:95], v171, s[4:5] offset:768
	v_mfma_f32_16x16x32_bf16 v[60:63], v[144:147], v[156:159], v[60:63]
	global_load_dwordx4 v[80:83], v172, s[0:1] offset:768
	v_mfma_f32_16x16x32_bf16 v[64:67], v[144:147], v[160:163], v[64:67]
	global_load_dwordx4 v[96:99], v172, s[4:5] offset:768
	s_waitcnt lgkmcnt(0)
	s_barrier
	v_mfma_f32_16x16x32_bf16 v[4:7], v[178:181], v[194:197], v[4:7]
	ds_read_b128 v[132:135], v165
	v_mfma_f32_16x16x32_bf16 v[8:11], v[178:181], v[198:201], v[8:11]
	ds_read_b128 v[148:151], v166 offset:32768
	v_mfma_f32_16x16x32_bf16 v[12:15], v[178:181], v[202:205], v[12:15]
	ds_read_b128 v[136:139], v165 offset:2048
	v_mfma_f32_16x16x32_bf16 v[16:19], v[178:181], v[206:209], v[16:19]
	ds_read_b128 v[152:155], v166 offset:34816
	v_mfma_f32_16x16x32_bf16 v[20:23], v[182:185], v[194:197], v[20:23]
	ds_read_b128 v[140:143], v165 offset:4096
	v_mfma_f32_16x16x32_bf16 v[24:27], v[182:185], v[198:201], v[24:27]
	ds_read_b128 v[156:159], v166 offset:36864
	v_mfma_f32_16x16x32_bf16 v[28:31], v[182:185], v[202:205], v[28:31]
	ds_read_b128 v[144:147], v165 offset:6144
	v_mfma_f32_16x16x32_bf16 v[32:35], v[182:185], v[206:209], v[32:35]
	ds_read_b128 v[160:163], v166 offset:38912
	v_mfma_f32_16x16x32_bf16 v[36:39], v[186:189], v[194:197], v[36:39]
	v_mfma_f32_16x16x32_bf16 v[40:43], v[186:189], v[198:201], v[40:43]
	v_mfma_f32_16x16x32_bf16 v[44:47], v[186:189], v[202:205], v[44:47]
	v_mfma_f32_16x16x32_bf16 v[48:51], v[186:189], v[206:209], v[48:51]
	v_mfma_f32_16x16x32_bf16 v[52:55], v[190:193], v[194:197], v[52:55]
	v_mfma_f32_16x16x32_bf16 v[56:59], v[190:193], v[198:201], v[56:59]
	v_mfma_f32_16x16x32_bf16 v[60:63], v[190:193], v[202:205], v[60:63]
	v_mfma_f32_16x16x32_bf16 v[64:67], v[190:193], v[206:209], v[64:67]
	s_waitcnt lgkmcnt(0)
	v_mfma_f32_16x16x32_bf16 v[4:7], v[132:135], v[148:151], v[4:7]
	ds_read_b128 v[178:181], v167
	s_waitcnt vmcnt(8)
	ds_write_b128 v164, v[100:103] offset:16384
	v_mfma_f32_16x16x32_bf16 v[8:11], v[132:135], v[152:155], v[8:11]
	ds_read_b128 v[194:197], v168 offset:32768
	ds_write_b128 v164, v[116:119] offset:49152
	v_mfma_f32_16x16x32_bf16 v[12:15], v[132:135], v[156:159], v[12:15]
	ds_read_b128 v[182:185], v167 offset:2048
	ds_write_b128 v164, v[104:107] offset:20480
	v_mfma_f32_16x16x32_bf16 v[16:19], v[132:135], v[160:163], v[16:19]
	ds_read_b128 v[198:201], v168 offset:34816
	ds_write_b128 v164, v[120:123] offset:53248
	v_mfma_f32_16x16x32_bf16 v[20:23], v[136:139], v[148:151], v[20:23]
	ds_read_b128 v[186:189], v167 offset:4096
	ds_write_b128 v164, v[108:111] offset:24576
	v_mfma_f32_16x16x32_bf16 v[24:27], v[136:139], v[152:155], v[24:27]
	ds_read_b128 v[202:205], v168 offset:36864
	ds_write_b128 v164, v[124:127] offset:57344
	v_mfma_f32_16x16x32_bf16 v[28:31], v[136:139], v[156:159], v[28:31]
	ds_read_b128 v[190:193], v167 offset:6144
	ds_write_b128 v164, v[112:115] offset:28672
	v_mfma_f32_16x16x32_bf16 v[32:35], v[136:139], v[160:163], v[32:35]
	ds_read_b128 v[206:209], v168 offset:38912
	ds_write_b128 v164, v[128:131] offset:61440
	v_mfma_f32_16x16x32_bf16 v[36:39], v[140:143], v[148:151], v[36:39]
	global_load_dwordx4 v[100:103], v169, s[0:1] offset:896
	v_mfma_f32_16x16x32_bf16 v[40:43], v[140:143], v[152:155], v[40:43]
	global_load_dwordx4 v[116:119], v169, s[4:5] offset:896
	v_mfma_f32_16x16x32_bf16 v[44:47], v[140:143], v[156:159], v[44:47]
	global_load_dwordx4 v[104:107], v170, s[0:1] offset:896
	v_mfma_f32_16x16x32_bf16 v[48:51], v[140:143], v[160:163], v[48:51]
	global_load_dwordx4 v[120:123], v170, s[4:5] offset:896
	v_mfma_f32_16x16x32_bf16 v[52:55], v[144:147], v[148:151], v[52:55]
	global_load_dwordx4 v[108:111], v171, s[0:1] offset:896
	v_mfma_f32_16x16x32_bf16 v[56:59], v[144:147], v[152:155], v[56:59]
	global_load_dwordx4 v[124:127], v171, s[4:5] offset:896
	v_mfma_f32_16x16x32_bf16 v[60:63], v[144:147], v[156:159], v[60:63]
	global_load_dwordx4 v[112:115], v172, s[0:1] offset:896
	v_mfma_f32_16x16x32_bf16 v[64:67], v[144:147], v[160:163], v[64:67]
	global_load_dwordx4 v[128:131], v172, s[4:5] offset:896
	s_waitcnt lgkmcnt(0)
	s_barrier
	v_mfma_f32_16x16x32_bf16 v[4:7], v[178:181], v[194:197], v[4:7]
	ds_read_b128 v[132:135], v165 offset:16384
	v_mfma_f32_16x16x32_bf16 v[8:11], v[178:181], v[198:201], v[8:11]
	ds_read_b128 v[148:151], v166 offset:49152
	v_mfma_f32_16x16x32_bf16 v[12:15], v[178:181], v[202:205], v[12:15]
	ds_read_b128 v[136:139], v165 offset:18432
	v_mfma_f32_16x16x32_bf16 v[16:19], v[178:181], v[206:209], v[16:19]
	ds_read_b128 v[152:155], v166 offset:51200
	v_mfma_f32_16x16x32_bf16 v[20:23], v[182:185], v[194:197], v[20:23]
	ds_read_b128 v[140:143], v165 offset:20480
	v_mfma_f32_16x16x32_bf16 v[24:27], v[182:185], v[198:201], v[24:27]
	ds_read_b128 v[156:159], v166 offset:53248
	v_mfma_f32_16x16x32_bf16 v[28:31], v[182:185], v[202:205], v[28:31]
	ds_read_b128 v[144:147], v165 offset:22528
	v_mfma_f32_16x16x32_bf16 v[32:35], v[182:185], v[206:209], v[32:35]
	ds_read_b128 v[160:163], v166 offset:55296
	v_mfma_f32_16x16x32_bf16 v[36:39], v[186:189], v[194:197], v[36:39]
	v_mfma_f32_16x16x32_bf16 v[40:43], v[186:189], v[198:201], v[40:43]
	v_mfma_f32_16x16x32_bf16 v[44:47], v[186:189], v[202:205], v[44:47]
	v_mfma_f32_16x16x32_bf16 v[48:51], v[186:189], v[206:209], v[48:51]
	v_mfma_f32_16x16x32_bf16 v[52:55], v[190:193], v[194:197], v[52:55]
	v_mfma_f32_16x16x32_bf16 v[56:59], v[190:193], v[198:201], v[56:59]
	v_mfma_f32_16x16x32_bf16 v[60:63], v[190:193], v[202:205], v[60:63]
	v_mfma_f32_16x16x32_bf16 v[64:67], v[190:193], v[206:209], v[64:67]
	s_waitcnt lgkmcnt(0)
	v_mfma_f32_16x16x32_bf16 v[4:7], v[132:135], v[148:151], v[4:7]
	ds_read_b128 v[178:181], v167 offset:16384
	s_waitcnt vmcnt(8)
	ds_write_b128 v164, v[68:71]
	v_mfma_f32_16x16x32_bf16 v[8:11], v[132:135], v[152:155], v[8:11]
	ds_read_b128 v[194:197], v168 offset:49152
	ds_write_b128 v164, v[84:87] offset:32768
	v_mfma_f32_16x16x32_bf16 v[12:15], v[132:135], v[156:159], v[12:15]
	ds_read_b128 v[182:185], v167 offset:18432
	ds_write_b128 v164, v[72:75] offset:4096
	v_mfma_f32_16x16x32_bf16 v[16:19], v[132:135], v[160:163], v[16:19]
	ds_read_b128 v[198:201], v168 offset:51200
	ds_write_b128 v164, v[88:91] offset:36864
	v_mfma_f32_16x16x32_bf16 v[20:23], v[136:139], v[148:151], v[20:23]
	ds_read_b128 v[186:189], v167 offset:20480
	ds_write_b128 v164, v[76:79] offset:8192
	v_mfma_f32_16x16x32_bf16 v[24:27], v[136:139], v[152:155], v[24:27]
	ds_read_b128 v[202:205], v168 offset:53248
	ds_write_b128 v164, v[92:95] offset:40960
	v_mfma_f32_16x16x32_bf16 v[28:31], v[136:139], v[156:159], v[28:31]
	ds_read_b128 v[190:193], v167 offset:22528
	ds_write_b128 v164, v[80:83] offset:12288
	v_mfma_f32_16x16x32_bf16 v[32:35], v[136:139], v[160:163], v[32:35]
	ds_read_b128 v[206:209], v168 offset:55296
	ds_write_b128 v164, v[96:99] offset:45056
	v_mfma_f32_16x16x32_bf16 v[36:39], v[140:143], v[148:151], v[36:39]
	global_load_dwordx4 v[68:71], v169, s[0:1] offset:1024
	v_mfma_f32_16x16x32_bf16 v[40:43], v[140:143], v[152:155], v[40:43]
	global_load_dwordx4 v[84:87], v169, s[4:5] offset:1024
	v_mfma_f32_16x16x32_bf16 v[44:47], v[140:143], v[156:159], v[44:47]
	global_load_dwordx4 v[72:75], v170, s[0:1] offset:1024
	v_mfma_f32_16x16x32_bf16 v[48:51], v[140:143], v[160:163], v[48:51]
	global_load_dwordx4 v[88:91], v170, s[4:5] offset:1024
	v_mfma_f32_16x16x32_bf16 v[52:55], v[144:147], v[148:151], v[52:55]
	global_load_dwordx4 v[76:79], v171, s[0:1] offset:1024
	v_mfma_f32_16x16x32_bf16 v[56:59], v[144:147], v[152:155], v[56:59]
	global_load_dwordx4 v[92:95], v171, s[4:5] offset:1024
	v_mfma_f32_16x16x32_bf16 v[60:63], v[144:147], v[156:159], v[60:63]
	global_load_dwordx4 v[80:83], v172, s[0:1] offset:1024
	v_mfma_f32_16x16x32_bf16 v[64:67], v[144:147], v[160:163], v[64:67]
	global_load_dwordx4 v[96:99], v172, s[4:5] offset:1024
	s_waitcnt lgkmcnt(0)
	s_barrier
	v_mfma_f32_16x16x32_bf16 v[4:7], v[178:181], v[194:197], v[4:7]
	ds_read_b128 v[132:135], v165
	v_mfma_f32_16x16x32_bf16 v[8:11], v[178:181], v[198:201], v[8:11]
	ds_read_b128 v[148:151], v166 offset:32768
	v_mfma_f32_16x16x32_bf16 v[12:15], v[178:181], v[202:205], v[12:15]
	ds_read_b128 v[136:139], v165 offset:2048
	v_mfma_f32_16x16x32_bf16 v[16:19], v[178:181], v[206:209], v[16:19]
	ds_read_b128 v[152:155], v166 offset:34816
	v_mfma_f32_16x16x32_bf16 v[20:23], v[182:185], v[194:197], v[20:23]
	ds_read_b128 v[140:143], v165 offset:4096
	v_mfma_f32_16x16x32_bf16 v[24:27], v[182:185], v[198:201], v[24:27]
	ds_read_b128 v[156:159], v166 offset:36864
	v_mfma_f32_16x16x32_bf16 v[28:31], v[182:185], v[202:205], v[28:31]
	ds_read_b128 v[144:147], v165 offset:6144
	v_mfma_f32_16x16x32_bf16 v[32:35], v[182:185], v[206:209], v[32:35]
	ds_read_b128 v[160:163], v166 offset:38912
	v_mfma_f32_16x16x32_bf16 v[36:39], v[186:189], v[194:197], v[36:39]
	v_mfma_f32_16x16x32_bf16 v[40:43], v[186:189], v[198:201], v[40:43]
	v_mfma_f32_16x16x32_bf16 v[44:47], v[186:189], v[202:205], v[44:47]
	v_mfma_f32_16x16x32_bf16 v[48:51], v[186:189], v[206:209], v[48:51]
	v_mfma_f32_16x16x32_bf16 v[52:55], v[190:193], v[194:197], v[52:55]
	v_mfma_f32_16x16x32_bf16 v[56:59], v[190:193], v[198:201], v[56:59]
	v_mfma_f32_16x16x32_bf16 v[60:63], v[190:193], v[202:205], v[60:63]
	v_mfma_f32_16x16x32_bf16 v[64:67], v[190:193], v[206:209], v[64:67]
	s_waitcnt lgkmcnt(0)
	v_mfma_f32_16x16x32_bf16 v[4:7], v[132:135], v[148:151], v[4:7]
	ds_read_b128 v[178:181], v167
	s_waitcnt vmcnt(8)
	ds_write_b128 v164, v[100:103] offset:16384
	v_mfma_f32_16x16x32_bf16 v[8:11], v[132:135], v[152:155], v[8:11]
	ds_read_b128 v[194:197], v168 offset:32768
	ds_write_b128 v164, v[116:119] offset:49152
	v_mfma_f32_16x16x32_bf16 v[12:15], v[132:135], v[156:159], v[12:15]
	ds_read_b128 v[182:185], v167 offset:2048
	ds_write_b128 v164, v[104:107] offset:20480
	v_mfma_f32_16x16x32_bf16 v[16:19], v[132:135], v[160:163], v[16:19]
	ds_read_b128 v[198:201], v168 offset:34816
	ds_write_b128 v164, v[120:123] offset:53248
	v_mfma_f32_16x16x32_bf16 v[20:23], v[136:139], v[148:151], v[20:23]
	ds_read_b128 v[186:189], v167 offset:4096
	ds_write_b128 v164, v[108:111] offset:24576
	v_mfma_f32_16x16x32_bf16 v[24:27], v[136:139], v[152:155], v[24:27]
	ds_read_b128 v[202:205], v168 offset:36864
	ds_write_b128 v164, v[124:127] offset:57344
	v_mfma_f32_16x16x32_bf16 v[28:31], v[136:139], v[156:159], v[28:31]
	ds_read_b128 v[190:193], v167 offset:6144
	ds_write_b128 v164, v[112:115] offset:28672
	v_mfma_f32_16x16x32_bf16 v[32:35], v[136:139], v[160:163], v[32:35]
	ds_read_b128 v[206:209], v168 offset:38912
	ds_write_b128 v164, v[128:131] offset:61440
	v_mfma_f32_16x16x32_bf16 v[36:39], v[140:143], v[148:151], v[36:39]
	global_load_dwordx4 v[100:103], v169, s[0:1] offset:1152
	v_mfma_f32_16x16x32_bf16 v[40:43], v[140:143], v[152:155], v[40:43]
	global_load_dwordx4 v[116:119], v169, s[4:5] offset:1152
	v_mfma_f32_16x16x32_bf16 v[44:47], v[140:143], v[156:159], v[44:47]
	global_load_dwordx4 v[104:107], v170, s[0:1] offset:1152
	v_mfma_f32_16x16x32_bf16 v[48:51], v[140:143], v[160:163], v[48:51]
	global_load_dwordx4 v[120:123], v170, s[4:5] offset:1152
	v_mfma_f32_16x16x32_bf16 v[52:55], v[144:147], v[148:151], v[52:55]
	global_load_dwordx4 v[108:111], v171, s[0:1] offset:1152
	v_mfma_f32_16x16x32_bf16 v[56:59], v[144:147], v[152:155], v[56:59]
	global_load_dwordx4 v[124:127], v171, s[4:5] offset:1152
	v_mfma_f32_16x16x32_bf16 v[60:63], v[144:147], v[156:159], v[60:63]
	global_load_dwordx4 v[112:115], v172, s[0:1] offset:1152
	v_mfma_f32_16x16x32_bf16 v[64:67], v[144:147], v[160:163], v[64:67]
	global_load_dwordx4 v[128:131], v172, s[4:5] offset:1152
	s_waitcnt lgkmcnt(0)
	s_barrier
	v_mfma_f32_16x16x32_bf16 v[4:7], v[178:181], v[194:197], v[4:7]
	ds_read_b128 v[132:135], v165 offset:16384
	v_mfma_f32_16x16x32_bf16 v[8:11], v[178:181], v[198:201], v[8:11]
	ds_read_b128 v[148:151], v166 offset:49152
	v_mfma_f32_16x16x32_bf16 v[12:15], v[178:181], v[202:205], v[12:15]
	ds_read_b128 v[136:139], v165 offset:18432
	v_mfma_f32_16x16x32_bf16 v[16:19], v[178:181], v[206:209], v[16:19]
	ds_read_b128 v[152:155], v166 offset:51200
	v_mfma_f32_16x16x32_bf16 v[20:23], v[182:185], v[194:197], v[20:23]
	ds_read_b128 v[140:143], v165 offset:20480
	v_mfma_f32_16x16x32_bf16 v[24:27], v[182:185], v[198:201], v[24:27]
	ds_read_b128 v[156:159], v166 offset:53248
	v_mfma_f32_16x16x32_bf16 v[28:31], v[182:185], v[202:205], v[28:31]
	ds_read_b128 v[144:147], v165 offset:22528
	v_mfma_f32_16x16x32_bf16 v[32:35], v[182:185], v[206:209], v[32:35]
	ds_read_b128 v[160:163], v166 offset:55296
	v_mfma_f32_16x16x32_bf16 v[36:39], v[186:189], v[194:197], v[36:39]
	v_mfma_f32_16x16x32_bf16 v[40:43], v[186:189], v[198:201], v[40:43]
	v_mfma_f32_16x16x32_bf16 v[44:47], v[186:189], v[202:205], v[44:47]
	v_mfma_f32_16x16x32_bf16 v[48:51], v[186:189], v[206:209], v[48:51]
	v_mfma_f32_16x16x32_bf16 v[52:55], v[190:193], v[194:197], v[52:55]
	v_mfma_f32_16x16x32_bf16 v[56:59], v[190:193], v[198:201], v[56:59]
	v_mfma_f32_16x16x32_bf16 v[60:63], v[190:193], v[202:205], v[60:63]
	v_mfma_f32_16x16x32_bf16 v[64:67], v[190:193], v[206:209], v[64:67]
	s_waitcnt lgkmcnt(0)
	v_mfma_f32_16x16x32_bf16 v[4:7], v[132:135], v[148:151], v[4:7]
	ds_read_b128 v[178:181], v167 offset:16384
	s_waitcnt vmcnt(8)
	ds_write_b128 v164, v[68:71]
	v_mfma_f32_16x16x32_bf16 v[8:11], v[132:135], v[152:155], v[8:11]
	ds_read_b128 v[194:197], v168 offset:49152
	ds_write_b128 v164, v[84:87] offset:32768
	v_mfma_f32_16x16x32_bf16 v[12:15], v[132:135], v[156:159], v[12:15]
	ds_read_b128 v[182:185], v167 offset:18432
	ds_write_b128 v164, v[72:75] offset:4096
	v_mfma_f32_16x16x32_bf16 v[16:19], v[132:135], v[160:163], v[16:19]
	ds_read_b128 v[198:201], v168 offset:51200
	ds_write_b128 v164, v[88:91] offset:36864
	v_mfma_f32_16x16x32_bf16 v[20:23], v[136:139], v[148:151], v[20:23]
	ds_read_b128 v[186:189], v167 offset:20480
	ds_write_b128 v164, v[76:79] offset:8192
	v_mfma_f32_16x16x32_bf16 v[24:27], v[136:139], v[152:155], v[24:27]
	ds_read_b128 v[202:205], v168 offset:53248
	ds_write_b128 v164, v[92:95] offset:40960
	v_mfma_f32_16x16x32_bf16 v[28:31], v[136:139], v[156:159], v[28:31]
	ds_read_b128 v[190:193], v167 offset:22528
	ds_write_b128 v164, v[80:83] offset:12288
	v_mfma_f32_16x16x32_bf16 v[32:35], v[136:139], v[160:163], v[32:35]
	ds_read_b128 v[206:209], v168 offset:55296
	ds_write_b128 v164, v[96:99] offset:45056
	v_mfma_f32_16x16x32_bf16 v[36:39], v[140:143], v[148:151], v[36:39]
	global_load_dwordx4 v[68:71], v169, s[0:1] offset:1280
	v_mfma_f32_16x16x32_bf16 v[40:43], v[140:143], v[152:155], v[40:43]
	global_load_dwordx4 v[84:87], v169, s[4:5] offset:1280
	v_mfma_f32_16x16x32_bf16 v[44:47], v[140:143], v[156:159], v[44:47]
	global_load_dwordx4 v[72:75], v170, s[0:1] offset:1280
	v_mfma_f32_16x16x32_bf16 v[48:51], v[140:143], v[160:163], v[48:51]
	global_load_dwordx4 v[88:91], v170, s[4:5] offset:1280
	v_mfma_f32_16x16x32_bf16 v[52:55], v[144:147], v[148:151], v[52:55]
	global_load_dwordx4 v[76:79], v171, s[0:1] offset:1280
	v_mfma_f32_16x16x32_bf16 v[56:59], v[144:147], v[152:155], v[56:59]
	global_load_dwordx4 v[92:95], v171, s[4:5] offset:1280
	v_mfma_f32_16x16x32_bf16 v[60:63], v[144:147], v[156:159], v[60:63]
	global_load_dwordx4 v[80:83], v172, s[0:1] offset:1280
	v_mfma_f32_16x16x32_bf16 v[64:67], v[144:147], v[160:163], v[64:67]
	global_load_dwordx4 v[96:99], v172, s[4:5] offset:1280
	s_waitcnt lgkmcnt(0)
	s_barrier
	v_mfma_f32_16x16x32_bf16 v[4:7], v[178:181], v[194:197], v[4:7]
	ds_read_b128 v[132:135], v165
	v_mfma_f32_16x16x32_bf16 v[8:11], v[178:181], v[198:201], v[8:11]
	ds_read_b128 v[148:151], v166 offset:32768
	v_mfma_f32_16x16x32_bf16 v[12:15], v[178:181], v[202:205], v[12:15]
	ds_read_b128 v[136:139], v165 offset:2048
	v_mfma_f32_16x16x32_bf16 v[16:19], v[178:181], v[206:209], v[16:19]
	ds_read_b128 v[152:155], v166 offset:34816
	v_mfma_f32_16x16x32_bf16 v[20:23], v[182:185], v[194:197], v[20:23]
	ds_read_b128 v[140:143], v165 offset:4096
	v_mfma_f32_16x16x32_bf16 v[24:27], v[182:185], v[198:201], v[24:27]
	ds_read_b128 v[156:159], v166 offset:36864
	v_mfma_f32_16x16x32_bf16 v[28:31], v[182:185], v[202:205], v[28:31]
	ds_read_b128 v[144:147], v165 offset:6144
	v_mfma_f32_16x16x32_bf16 v[32:35], v[182:185], v[206:209], v[32:35]
	ds_read_b128 v[160:163], v166 offset:38912
	v_mfma_f32_16x16x32_bf16 v[36:39], v[186:189], v[194:197], v[36:39]
	v_mfma_f32_16x16x32_bf16 v[40:43], v[186:189], v[198:201], v[40:43]
	v_mfma_f32_16x16x32_bf16 v[44:47], v[186:189], v[202:205], v[44:47]
	v_mfma_f32_16x16x32_bf16 v[48:51], v[186:189], v[206:209], v[48:51]
	v_mfma_f32_16x16x32_bf16 v[52:55], v[190:193], v[194:197], v[52:55]
	v_mfma_f32_16x16x32_bf16 v[56:59], v[190:193], v[198:201], v[56:59]
	v_mfma_f32_16x16x32_bf16 v[60:63], v[190:193], v[202:205], v[60:63]
	v_mfma_f32_16x16x32_bf16 v[64:67], v[190:193], v[206:209], v[64:67]
	s_waitcnt lgkmcnt(0)
	v_mfma_f32_16x16x32_bf16 v[4:7], v[132:135], v[148:151], v[4:7]
	ds_read_b128 v[178:181], v167
	s_waitcnt vmcnt(8)
	ds_write_b128 v164, v[100:103] offset:16384
	v_mfma_f32_16x16x32_bf16 v[8:11], v[132:135], v[152:155], v[8:11]
	ds_read_b128 v[194:197], v168 offset:32768
	ds_write_b128 v164, v[116:119] offset:49152
	v_mfma_f32_16x16x32_bf16 v[12:15], v[132:135], v[156:159], v[12:15]
	ds_read_b128 v[182:185], v167 offset:2048
	ds_write_b128 v164, v[104:107] offset:20480
	v_mfma_f32_16x16x32_bf16 v[16:19], v[132:135], v[160:163], v[16:19]
	ds_read_b128 v[198:201], v168 offset:34816
	ds_write_b128 v164, v[120:123] offset:53248
	v_mfma_f32_16x16x32_bf16 v[20:23], v[136:139], v[148:151], v[20:23]
	ds_read_b128 v[186:189], v167 offset:4096
	ds_write_b128 v164, v[108:111] offset:24576
	v_mfma_f32_16x16x32_bf16 v[24:27], v[136:139], v[152:155], v[24:27]
	ds_read_b128 v[202:205], v168 offset:36864
	ds_write_b128 v164, v[124:127] offset:57344
	v_mfma_f32_16x16x32_bf16 v[28:31], v[136:139], v[156:159], v[28:31]
	ds_read_b128 v[190:193], v167 offset:6144
	ds_write_b128 v164, v[112:115] offset:28672
	v_mfma_f32_16x16x32_bf16 v[32:35], v[136:139], v[160:163], v[32:35]
	ds_read_b128 v[206:209], v168 offset:38912
	ds_write_b128 v164, v[128:131] offset:61440
	v_mfma_f32_16x16x32_bf16 v[36:39], v[140:143], v[148:151], v[36:39]
	global_load_dwordx4 v[100:103], v169, s[0:1] offset:1408
	v_mfma_f32_16x16x32_bf16 v[40:43], v[140:143], v[152:155], v[40:43]
	global_load_dwordx4 v[116:119], v169, s[4:5] offset:1408
	v_mfma_f32_16x16x32_bf16 v[44:47], v[140:143], v[156:159], v[44:47]
	global_load_dwordx4 v[104:107], v170, s[0:1] offset:1408
	v_mfma_f32_16x16x32_bf16 v[48:51], v[140:143], v[160:163], v[48:51]
	global_load_dwordx4 v[120:123], v170, s[4:5] offset:1408
	v_mfma_f32_16x16x32_bf16 v[52:55], v[144:147], v[148:151], v[52:55]
	global_load_dwordx4 v[108:111], v171, s[0:1] offset:1408
	v_mfma_f32_16x16x32_bf16 v[56:59], v[144:147], v[152:155], v[56:59]
	global_load_dwordx4 v[124:127], v171, s[4:5] offset:1408
	v_mfma_f32_16x16x32_bf16 v[60:63], v[144:147], v[156:159], v[60:63]
	global_load_dwordx4 v[112:115], v172, s[0:1] offset:1408
	v_mfma_f32_16x16x32_bf16 v[64:67], v[144:147], v[160:163], v[64:67]
	global_load_dwordx4 v[128:131], v172, s[4:5] offset:1408
	s_waitcnt lgkmcnt(0)
	s_barrier
	v_mfma_f32_16x16x32_bf16 v[4:7], v[178:181], v[194:197], v[4:7]
	ds_read_b128 v[132:135], v165 offset:16384
	v_mfma_f32_16x16x32_bf16 v[8:11], v[178:181], v[198:201], v[8:11]
	ds_read_b128 v[148:151], v166 offset:49152
	v_mfma_f32_16x16x32_bf16 v[12:15], v[178:181], v[202:205], v[12:15]
	ds_read_b128 v[136:139], v165 offset:18432
	v_mfma_f32_16x16x32_bf16 v[16:19], v[178:181], v[206:209], v[16:19]
	ds_read_b128 v[152:155], v166 offset:51200
	v_mfma_f32_16x16x32_bf16 v[20:23], v[182:185], v[194:197], v[20:23]
	ds_read_b128 v[140:143], v165 offset:20480
	v_mfma_f32_16x16x32_bf16 v[24:27], v[182:185], v[198:201], v[24:27]
	ds_read_b128 v[156:159], v166 offset:53248
	v_mfma_f32_16x16x32_bf16 v[28:31], v[182:185], v[202:205], v[28:31]
	ds_read_b128 v[144:147], v165 offset:22528
	v_mfma_f32_16x16x32_bf16 v[32:35], v[182:185], v[206:209], v[32:35]
	ds_read_b128 v[160:163], v166 offset:55296
	v_mfma_f32_16x16x32_bf16 v[36:39], v[186:189], v[194:197], v[36:39]
	v_mfma_f32_16x16x32_bf16 v[40:43], v[186:189], v[198:201], v[40:43]
	v_mfma_f32_16x16x32_bf16 v[44:47], v[186:189], v[202:205], v[44:47]
	v_mfma_f32_16x16x32_bf16 v[48:51], v[186:189], v[206:209], v[48:51]
	v_mfma_f32_16x16x32_bf16 v[52:55], v[190:193], v[194:197], v[52:55]
	v_mfma_f32_16x16x32_bf16 v[56:59], v[190:193], v[198:201], v[56:59]
	v_mfma_f32_16x16x32_bf16 v[60:63], v[190:193], v[202:205], v[60:63]
	v_mfma_f32_16x16x32_bf16 v[64:67], v[190:193], v[206:209], v[64:67]
	s_waitcnt lgkmcnt(0)
	v_mfma_f32_16x16x32_bf16 v[4:7], v[132:135], v[148:151], v[4:7]
	ds_read_b128 v[178:181], v167 offset:16384
	s_waitcnt vmcnt(8)
	ds_write_b128 v164, v[68:71]
	v_mfma_f32_16x16x32_bf16 v[8:11], v[132:135], v[152:155], v[8:11]
	ds_read_b128 v[194:197], v168 offset:49152
	ds_write_b128 v164, v[84:87] offset:32768
	v_mfma_f32_16x16x32_bf16 v[12:15], v[132:135], v[156:159], v[12:15]
	ds_read_b128 v[182:185], v167 offset:18432
	ds_write_b128 v164, v[72:75] offset:4096
	v_mfma_f32_16x16x32_bf16 v[16:19], v[132:135], v[160:163], v[16:19]
	ds_read_b128 v[198:201], v168 offset:51200
	ds_write_b128 v164, v[88:91] offset:36864
	v_mfma_f32_16x16x32_bf16 v[20:23], v[136:139], v[148:151], v[20:23]
	ds_read_b128 v[186:189], v167 offset:20480
	ds_write_b128 v164, v[76:79] offset:8192
	v_mfma_f32_16x16x32_bf16 v[24:27], v[136:139], v[152:155], v[24:27]
	ds_read_b128 v[202:205], v168 offset:53248
	ds_write_b128 v164, v[92:95] offset:40960
	v_mfma_f32_16x16x32_bf16 v[28:31], v[136:139], v[156:159], v[28:31]
	ds_read_b128 v[190:193], v167 offset:22528
	ds_write_b128 v164, v[80:83] offset:12288
	v_mfma_f32_16x16x32_bf16 v[32:35], v[136:139], v[160:163], v[32:35]
	ds_read_b128 v[206:209], v168 offset:55296
	ds_write_b128 v164, v[96:99] offset:45056
	v_mfma_f32_16x16x32_bf16 v[36:39], v[140:143], v[148:151], v[36:39]
	global_load_dwordx4 v[68:71], v169, s[0:1] offset:1536
	v_mfma_f32_16x16x32_bf16 v[40:43], v[140:143], v[152:155], v[40:43]
	global_load_dwordx4 v[84:87], v169, s[4:5] offset:1536
	v_mfma_f32_16x16x32_bf16 v[44:47], v[140:143], v[156:159], v[44:47]
	global_load_dwordx4 v[72:75], v170, s[0:1] offset:1536
	v_mfma_f32_16x16x32_bf16 v[48:51], v[140:143], v[160:163], v[48:51]
	global_load_dwordx4 v[88:91], v170, s[4:5] offset:1536
	v_mfma_f32_16x16x32_bf16 v[52:55], v[144:147], v[148:151], v[52:55]
	global_load_dwordx4 v[76:79], v171, s[0:1] offset:1536
	v_mfma_f32_16x16x32_bf16 v[56:59], v[144:147], v[152:155], v[56:59]
	global_load_dwordx4 v[92:95], v171, s[4:5] offset:1536
	v_mfma_f32_16x16x32_bf16 v[60:63], v[144:147], v[156:159], v[60:63]
	global_load_dwordx4 v[80:83], v172, s[0:1] offset:1536
	v_mfma_f32_16x16x32_bf16 v[64:67], v[144:147], v[160:163], v[64:67]
	global_load_dwordx4 v[96:99], v172, s[4:5] offset:1536
	s_waitcnt lgkmcnt(0)
	s_barrier
	v_mfma_f32_16x16x32_bf16 v[4:7], v[178:181], v[194:197], v[4:7]
	ds_read_b128 v[132:135], v165
	v_mfma_f32_16x16x32_bf16 v[8:11], v[178:181], v[198:201], v[8:11]
	ds_read_b128 v[148:151], v166 offset:32768
	v_mfma_f32_16x16x32_bf16 v[12:15], v[178:181], v[202:205], v[12:15]
	ds_read_b128 v[136:139], v165 offset:2048
	v_mfma_f32_16x16x32_bf16 v[16:19], v[178:181], v[206:209], v[16:19]
	ds_read_b128 v[152:155], v166 offset:34816
	v_mfma_f32_16x16x32_bf16 v[20:23], v[182:185], v[194:197], v[20:23]
	ds_read_b128 v[140:143], v165 offset:4096
	v_mfma_f32_16x16x32_bf16 v[24:27], v[182:185], v[198:201], v[24:27]
	ds_read_b128 v[156:159], v166 offset:36864
	v_mfma_f32_16x16x32_bf16 v[28:31], v[182:185], v[202:205], v[28:31]
	ds_read_b128 v[144:147], v165 offset:6144
	v_mfma_f32_16x16x32_bf16 v[32:35], v[182:185], v[206:209], v[32:35]
	ds_read_b128 v[160:163], v166 offset:38912
	v_mfma_f32_16x16x32_bf16 v[36:39], v[186:189], v[194:197], v[36:39]
	v_mfma_f32_16x16x32_bf16 v[40:43], v[186:189], v[198:201], v[40:43]
	v_mfma_f32_16x16x32_bf16 v[44:47], v[186:189], v[202:205], v[44:47]
	v_mfma_f32_16x16x32_bf16 v[48:51], v[186:189], v[206:209], v[48:51]
	v_mfma_f32_16x16x32_bf16 v[52:55], v[190:193], v[194:197], v[52:55]
	v_mfma_f32_16x16x32_bf16 v[56:59], v[190:193], v[198:201], v[56:59]
	v_mfma_f32_16x16x32_bf16 v[60:63], v[190:193], v[202:205], v[60:63]
	v_mfma_f32_16x16x32_bf16 v[64:67], v[190:193], v[206:209], v[64:67]
	s_waitcnt lgkmcnt(0)
	v_mfma_f32_16x16x32_bf16 v[4:7], v[132:135], v[148:151], v[4:7]
	ds_read_b128 v[178:181], v167
	s_waitcnt vmcnt(8)
	ds_write_b128 v164, v[100:103] offset:16384
	v_mfma_f32_16x16x32_bf16 v[8:11], v[132:135], v[152:155], v[8:11]
	ds_read_b128 v[194:197], v168 offset:32768
	ds_write_b128 v164, v[116:119] offset:49152
	v_mfma_f32_16x16x32_bf16 v[12:15], v[132:135], v[156:159], v[12:15]
	ds_read_b128 v[182:185], v167 offset:2048
	ds_write_b128 v164, v[104:107] offset:20480
	v_mfma_f32_16x16x32_bf16 v[16:19], v[132:135], v[160:163], v[16:19]
	ds_read_b128 v[198:201], v168 offset:34816
	ds_write_b128 v164, v[120:123] offset:53248
	v_mfma_f32_16x16x32_bf16 v[20:23], v[136:139], v[148:151], v[20:23]
	ds_read_b128 v[186:189], v167 offset:4096
	ds_write_b128 v164, v[108:111] offset:24576
	v_mfma_f32_16x16x32_bf16 v[24:27], v[136:139], v[152:155], v[24:27]
	ds_read_b128 v[202:205], v168 offset:36864
	ds_write_b128 v164, v[124:127] offset:57344
	v_mfma_f32_16x16x32_bf16 v[28:31], v[136:139], v[156:159], v[28:31]
	ds_read_b128 v[190:193], v167 offset:6144
	ds_write_b128 v164, v[112:115] offset:28672
	v_mfma_f32_16x16x32_bf16 v[32:35], v[136:139], v[160:163], v[32:35]
	ds_read_b128 v[206:209], v168 offset:38912
	ds_write_b128 v164, v[128:131] offset:61440
	v_mfma_f32_16x16x32_bf16 v[36:39], v[140:143], v[148:151], v[36:39]
	global_load_dwordx4 v[100:103], v169, s[0:1] offset:1664
	v_mfma_f32_16x16x32_bf16 v[40:43], v[140:143], v[152:155], v[40:43]
	global_load_dwordx4 v[116:119], v169, s[4:5] offset:1664
	v_mfma_f32_16x16x32_bf16 v[44:47], v[140:143], v[156:159], v[44:47]
	global_load_dwordx4 v[104:107], v170, s[0:1] offset:1664
	v_mfma_f32_16x16x32_bf16 v[48:51], v[140:143], v[160:163], v[48:51]
	global_load_dwordx4 v[120:123], v170, s[4:5] offset:1664
	v_mfma_f32_16x16x32_bf16 v[52:55], v[144:147], v[148:151], v[52:55]
	global_load_dwordx4 v[108:111], v171, s[0:1] offset:1664
	v_mfma_f32_16x16x32_bf16 v[56:59], v[144:147], v[152:155], v[56:59]
	global_load_dwordx4 v[124:127], v171, s[4:5] offset:1664
	v_mfma_f32_16x16x32_bf16 v[60:63], v[144:147], v[156:159], v[60:63]
	global_load_dwordx4 v[112:115], v172, s[0:1] offset:1664
	v_mfma_f32_16x16x32_bf16 v[64:67], v[144:147], v[160:163], v[64:67]
	global_load_dwordx4 v[128:131], v172, s[4:5] offset:1664
	s_waitcnt lgkmcnt(0)
	s_barrier
	v_mfma_f32_16x16x32_bf16 v[4:7], v[178:181], v[194:197], v[4:7]
	ds_read_b128 v[132:135], v165 offset:16384
	v_mfma_f32_16x16x32_bf16 v[8:11], v[178:181], v[198:201], v[8:11]
	ds_read_b128 v[148:151], v166 offset:49152
	v_mfma_f32_16x16x32_bf16 v[12:15], v[178:181], v[202:205], v[12:15]
	ds_read_b128 v[136:139], v165 offset:18432
	v_mfma_f32_16x16x32_bf16 v[16:19], v[178:181], v[206:209], v[16:19]
	ds_read_b128 v[152:155], v166 offset:51200
	v_mfma_f32_16x16x32_bf16 v[20:23], v[182:185], v[194:197], v[20:23]
	ds_read_b128 v[140:143], v165 offset:20480
	v_mfma_f32_16x16x32_bf16 v[24:27], v[182:185], v[198:201], v[24:27]
	ds_read_b128 v[156:159], v166 offset:53248
	v_mfma_f32_16x16x32_bf16 v[28:31], v[182:185], v[202:205], v[28:31]
	ds_read_b128 v[144:147], v165 offset:22528
	v_mfma_f32_16x16x32_bf16 v[32:35], v[182:185], v[206:209], v[32:35]
	ds_read_b128 v[160:163], v166 offset:55296
	v_mfma_f32_16x16x32_bf16 v[36:39], v[186:189], v[194:197], v[36:39]
	v_mfma_f32_16x16x32_bf16 v[40:43], v[186:189], v[198:201], v[40:43]
	v_mfma_f32_16x16x32_bf16 v[44:47], v[186:189], v[202:205], v[44:47]
	v_mfma_f32_16x16x32_bf16 v[48:51], v[186:189], v[206:209], v[48:51]
	v_mfma_f32_16x16x32_bf16 v[52:55], v[190:193], v[194:197], v[52:55]
	v_mfma_f32_16x16x32_bf16 v[56:59], v[190:193], v[198:201], v[56:59]
	v_mfma_f32_16x16x32_bf16 v[60:63], v[190:193], v[202:205], v[60:63]
	v_mfma_f32_16x16x32_bf16 v[64:67], v[190:193], v[206:209], v[64:67]
	s_waitcnt lgkmcnt(0)
	v_mfma_f32_16x16x32_bf16 v[4:7], v[132:135], v[148:151], v[4:7]
	ds_read_b128 v[178:181], v167 offset:16384
	s_waitcnt vmcnt(8)
	ds_write_b128 v164, v[68:71]
	v_mfma_f32_16x16x32_bf16 v[8:11], v[132:135], v[152:155], v[8:11]
	ds_read_b128 v[194:197], v168 offset:49152
	ds_write_b128 v164, v[84:87] offset:32768
	v_mfma_f32_16x16x32_bf16 v[12:15], v[132:135], v[156:159], v[12:15]
	ds_read_b128 v[182:185], v167 offset:18432
	ds_write_b128 v164, v[72:75] offset:4096
	v_mfma_f32_16x16x32_bf16 v[16:19], v[132:135], v[160:163], v[16:19]
	ds_read_b128 v[198:201], v168 offset:51200
	ds_write_b128 v164, v[88:91] offset:36864
	v_mfma_f32_16x16x32_bf16 v[20:23], v[136:139], v[148:151], v[20:23]
	ds_read_b128 v[186:189], v167 offset:20480
	ds_write_b128 v164, v[76:79] offset:8192
	v_mfma_f32_16x16x32_bf16 v[24:27], v[136:139], v[152:155], v[24:27]
	ds_read_b128 v[202:205], v168 offset:53248
	ds_write_b128 v164, v[92:95] offset:40960
	v_mfma_f32_16x16x32_bf16 v[28:31], v[136:139], v[156:159], v[28:31]
	ds_read_b128 v[190:193], v167 offset:22528
	ds_write_b128 v164, v[80:83] offset:12288
	v_mfma_f32_16x16x32_bf16 v[32:35], v[136:139], v[160:163], v[32:35]
	ds_read_b128 v[206:209], v168 offset:55296
	ds_write_b128 v164, v[96:99] offset:45056
	v_mfma_f32_16x16x32_bf16 v[36:39], v[140:143], v[148:151], v[36:39]
	global_load_dwordx4 v[68:71], v169, s[0:1] offset:1792
	v_mfma_f32_16x16x32_bf16 v[40:43], v[140:143], v[152:155], v[40:43]
	global_load_dwordx4 v[84:87], v169, s[4:5] offset:1792
	v_mfma_f32_16x16x32_bf16 v[44:47], v[140:143], v[156:159], v[44:47]
	global_load_dwordx4 v[72:75], v170, s[0:1] offset:1792
	v_mfma_f32_16x16x32_bf16 v[48:51], v[140:143], v[160:163], v[48:51]
	global_load_dwordx4 v[88:91], v170, s[4:5] offset:1792
	v_mfma_f32_16x16x32_bf16 v[52:55], v[144:147], v[148:151], v[52:55]
	global_load_dwordx4 v[76:79], v171, s[0:1] offset:1792
	v_mfma_f32_16x16x32_bf16 v[56:59], v[144:147], v[152:155], v[56:59]
	global_load_dwordx4 v[92:95], v171, s[4:5] offset:1792
	v_mfma_f32_16x16x32_bf16 v[60:63], v[144:147], v[156:159], v[60:63]
	global_load_dwordx4 v[80:83], v172, s[0:1] offset:1792
	v_mfma_f32_16x16x32_bf16 v[64:67], v[144:147], v[160:163], v[64:67]
	global_load_dwordx4 v[96:99], v172, s[4:5] offset:1792
	s_waitcnt lgkmcnt(0)
	s_barrier
	v_mfma_f32_16x16x32_bf16 v[4:7], v[178:181], v[194:197], v[4:7]
	ds_read_b128 v[132:135], v165
	v_mfma_f32_16x16x32_bf16 v[8:11], v[178:181], v[198:201], v[8:11]
	ds_read_b128 v[148:151], v166 offset:32768
	v_mfma_f32_16x16x32_bf16 v[12:15], v[178:181], v[202:205], v[12:15]
	ds_read_b128 v[136:139], v165 offset:2048
	v_mfma_f32_16x16x32_bf16 v[16:19], v[178:181], v[206:209], v[16:19]
	ds_read_b128 v[152:155], v166 offset:34816
	v_mfma_f32_16x16x32_bf16 v[20:23], v[182:185], v[194:197], v[20:23]
	ds_read_b128 v[140:143], v165 offset:4096
	v_mfma_f32_16x16x32_bf16 v[24:27], v[182:185], v[198:201], v[24:27]
	ds_read_b128 v[156:159], v166 offset:36864
	v_mfma_f32_16x16x32_bf16 v[28:31], v[182:185], v[202:205], v[28:31]
	ds_read_b128 v[144:147], v165 offset:6144
	v_mfma_f32_16x16x32_bf16 v[32:35], v[182:185], v[206:209], v[32:35]
	ds_read_b128 v[160:163], v166 offset:38912
	v_mfma_f32_16x16x32_bf16 v[36:39], v[186:189], v[194:197], v[36:39]
	v_mfma_f32_16x16x32_bf16 v[40:43], v[186:189], v[198:201], v[40:43]
	v_mfma_f32_16x16x32_bf16 v[44:47], v[186:189], v[202:205], v[44:47]
	v_mfma_f32_16x16x32_bf16 v[48:51], v[186:189], v[206:209], v[48:51]
	v_mfma_f32_16x16x32_bf16 v[52:55], v[190:193], v[194:197], v[52:55]
	v_mfma_f32_16x16x32_bf16 v[56:59], v[190:193], v[198:201], v[56:59]
	v_mfma_f32_16x16x32_bf16 v[60:63], v[190:193], v[202:205], v[60:63]
	v_mfma_f32_16x16x32_bf16 v[64:67], v[190:193], v[206:209], v[64:67]
	s_waitcnt lgkmcnt(0)
	v_mfma_f32_16x16x32_bf16 v[4:7], v[132:135], v[148:151], v[4:7]
	ds_read_b128 v[178:181], v167
	s_waitcnt vmcnt(8)
	ds_write_b128 v164, v[100:103] offset:16384
	v_mfma_f32_16x16x32_bf16 v[8:11], v[132:135], v[152:155], v[8:11]
	ds_read_b128 v[194:197], v168 offset:32768
	ds_write_b128 v164, v[116:119] offset:49152
	v_mfma_f32_16x16x32_bf16 v[12:15], v[132:135], v[156:159], v[12:15]
	ds_read_b128 v[182:185], v167 offset:2048
	ds_write_b128 v164, v[104:107] offset:20480
	v_mfma_f32_16x16x32_bf16 v[16:19], v[132:135], v[160:163], v[16:19]
	ds_read_b128 v[198:201], v168 offset:34816
	ds_write_b128 v164, v[120:123] offset:53248
	v_mfma_f32_16x16x32_bf16 v[20:23], v[136:139], v[148:151], v[20:23]
	ds_read_b128 v[186:189], v167 offset:4096
	ds_write_b128 v164, v[108:111] offset:24576
	v_mfma_f32_16x16x32_bf16 v[24:27], v[136:139], v[152:155], v[24:27]
	ds_read_b128 v[202:205], v168 offset:36864
	ds_write_b128 v164, v[124:127] offset:57344
	v_mfma_f32_16x16x32_bf16 v[28:31], v[136:139], v[156:159], v[28:31]
	ds_read_b128 v[190:193], v167 offset:6144
	ds_write_b128 v164, v[112:115] offset:28672
	v_mfma_f32_16x16x32_bf16 v[32:35], v[136:139], v[160:163], v[32:35]
	ds_read_b128 v[206:209], v168 offset:38912
	ds_write_b128 v164, v[128:131] offset:61440
	v_mfma_f32_16x16x32_bf16 v[36:39], v[140:143], v[148:151], v[36:39]
	global_load_dwordx4 v[100:103], v169, s[0:1] offset:1920
	v_mfma_f32_16x16x32_bf16 v[40:43], v[140:143], v[152:155], v[40:43]
	global_load_dwordx4 v[116:119], v169, s[4:5] offset:1920
	v_mfma_f32_16x16x32_bf16 v[44:47], v[140:143], v[156:159], v[44:47]
	global_load_dwordx4 v[104:107], v170, s[0:1] offset:1920
	v_mfma_f32_16x16x32_bf16 v[48:51], v[140:143], v[160:163], v[48:51]
	global_load_dwordx4 v[120:123], v170, s[4:5] offset:1920
	v_mfma_f32_16x16x32_bf16 v[52:55], v[144:147], v[148:151], v[52:55]
	global_load_dwordx4 v[108:111], v171, s[0:1] offset:1920
	v_mfma_f32_16x16x32_bf16 v[56:59], v[144:147], v[152:155], v[56:59]
	global_load_dwordx4 v[124:127], v171, s[4:5] offset:1920
	v_mfma_f32_16x16x32_bf16 v[60:63], v[144:147], v[156:159], v[60:63]
	global_load_dwordx4 v[112:115], v172, s[0:1] offset:1920
	v_mfma_f32_16x16x32_bf16 v[64:67], v[144:147], v[160:163], v[64:67]
	global_load_dwordx4 v[128:131], v172, s[4:5] offset:1920
	s_waitcnt lgkmcnt(0)
	s_barrier
	v_mfma_f32_16x16x32_bf16 v[4:7], v[178:181], v[194:197], v[4:7]
	ds_read_b128 v[132:135], v165 offset:16384
	v_mfma_f32_16x16x32_bf16 v[8:11], v[178:181], v[198:201], v[8:11]
	ds_read_b128 v[148:151], v166 offset:49152
	v_mfma_f32_16x16x32_bf16 v[12:15], v[178:181], v[202:205], v[12:15]
	ds_read_b128 v[136:139], v165 offset:18432
	v_mfma_f32_16x16x32_bf16 v[16:19], v[178:181], v[206:209], v[16:19]
	ds_read_b128 v[152:155], v166 offset:51200
	v_mfma_f32_16x16x32_bf16 v[20:23], v[182:185], v[194:197], v[20:23]
	ds_read_b128 v[140:143], v165 offset:20480
	v_mfma_f32_16x16x32_bf16 v[24:27], v[182:185], v[198:201], v[24:27]
	ds_read_b128 v[156:159], v166 offset:53248
	v_mfma_f32_16x16x32_bf16 v[28:31], v[182:185], v[202:205], v[28:31]
	ds_read_b128 v[144:147], v165 offset:22528
	v_mfma_f32_16x16x32_bf16 v[32:35], v[182:185], v[206:209], v[32:35]
	ds_read_b128 v[160:163], v166 offset:55296
	v_mfma_f32_16x16x32_bf16 v[36:39], v[186:189], v[194:197], v[36:39]
	v_mfma_f32_16x16x32_bf16 v[40:43], v[186:189], v[198:201], v[40:43]
	v_mfma_f32_16x16x32_bf16 v[44:47], v[186:189], v[202:205], v[44:47]
	v_mfma_f32_16x16x32_bf16 v[48:51], v[186:189], v[206:209], v[48:51]
	v_mfma_f32_16x16x32_bf16 v[52:55], v[190:193], v[194:197], v[52:55]
	v_mfma_f32_16x16x32_bf16 v[56:59], v[190:193], v[198:201], v[56:59]
	v_mfma_f32_16x16x32_bf16 v[60:63], v[190:193], v[202:205], v[60:63]
	v_mfma_f32_16x16x32_bf16 v[64:67], v[190:193], v[206:209], v[64:67]
	s_waitcnt lgkmcnt(0)
	s_add_i32 s12, s10, s13
	s_cmp_lt_u32 s12, 272
	s_cselect_b32 vcc_lo, s12, s10
	s_and_b32 s12, vcc_lo, 7
	s_lshr_b32 s22, vcc_lo, 3
	s_add_i32 s22, s22, s11
	s_lshl_b32 s12, s12, 18
	s_lshl_b32 s22, s22, 18
	s_add_u32 s0, s8, s12
	s_addc_u32 s1, s9, 0
	s_add_u32 s4, s20, s22
	s_addc_u32 s5, s21, 0
	v_mfma_f32_16x16x32_bf16 v[4:7], v[132:135], v[148:151], v[4:7]
	ds_read_b128 v[178:181], v167 offset:16384
	s_waitcnt vmcnt(8)
	ds_write_b128 v164, v[68:71]
	v_mfma_f32_16x16x32_bf16 v[8:11], v[132:135], v[152:155], v[8:11]
	ds_read_b128 v[194:197], v168 offset:49152
	ds_write_b128 v164, v[84:87] offset:32768
	v_mfma_f32_16x16x32_bf16 v[12:15], v[132:135], v[156:159], v[12:15]
	ds_read_b128 v[182:185], v167 offset:18432
	ds_write_b128 v164, v[72:75] offset:4096
	v_mfma_f32_16x16x32_bf16 v[16:19], v[132:135], v[160:163], v[16:19]
	ds_read_b128 v[198:201], v168 offset:51200
	ds_write_b128 v164, v[88:91] offset:36864
	v_mfma_f32_16x16x32_bf16 v[20:23], v[136:139], v[148:151], v[20:23]
	ds_read_b128 v[186:189], v167 offset:20480
	ds_write_b128 v164, v[76:79] offset:8192
	v_mfma_f32_16x16x32_bf16 v[24:27], v[136:139], v[152:155], v[24:27]
	ds_read_b128 v[202:205], v168 offset:53248
	ds_write_b128 v164, v[92:95] offset:40960
	v_mfma_f32_16x16x32_bf16 v[28:31], v[136:139], v[156:159], v[28:31]
	ds_read_b128 v[190:193], v167 offset:22528
	ds_write_b128 v164, v[80:83] offset:12288
	v_mfma_f32_16x16x32_bf16 v[32:35], v[136:139], v[160:163], v[32:35]
	ds_read_b128 v[206:209], v168 offset:55296
	ds_write_b128 v164, v[96:99] offset:45056
	v_mfma_f32_16x16x32_bf16 v[36:39], v[140:143], v[148:151], v[36:39]
	global_load_dwordx4 v[68:71], v169, s[0:1]
	v_mfma_f32_16x16x32_bf16 v[40:43], v[140:143], v[152:155], v[40:43]
	global_load_dwordx4 v[84:87], v169, s[4:5]
	v_mfma_f32_16x16x32_bf16 v[44:47], v[140:143], v[156:159], v[44:47]
	global_load_dwordx4 v[72:75], v170, s[0:1]
	v_mfma_f32_16x16x32_bf16 v[48:51], v[140:143], v[160:163], v[48:51]
	global_load_dwordx4 v[88:91], v170, s[4:5]
	v_mfma_f32_16x16x32_bf16 v[52:55], v[144:147], v[148:151], v[52:55]
	global_load_dwordx4 v[76:79], v171, s[0:1]
	v_mfma_f32_16x16x32_bf16 v[56:59], v[144:147], v[152:155], v[56:59]
	global_load_dwordx4 v[92:95], v171, s[4:5]
	v_mfma_f32_16x16x32_bf16 v[60:63], v[144:147], v[156:159], v[60:63]
	global_load_dwordx4 v[80:83], v172, s[0:1]
	v_mfma_f32_16x16x32_bf16 v[64:67], v[144:147], v[160:163], v[64:67]
	global_load_dwordx4 v[96:99], v172, s[4:5]
	s_waitcnt lgkmcnt(0)
	s_barrier
	v_mfma_f32_16x16x32_bf16 v[4:7], v[178:181], v[194:197], v[4:7]
	ds_read_b128 v[132:135], v165
	v_mfma_f32_16x16x32_bf16 v[8:11], v[178:181], v[198:201], v[8:11]
	ds_read_b128 v[148:151], v166 offset:32768
	v_mfma_f32_16x16x32_bf16 v[12:15], v[178:181], v[202:205], v[12:15]
	ds_read_b128 v[136:139], v165 offset:2048
	v_mfma_f32_16x16x32_bf16 v[16:19], v[178:181], v[206:209], v[16:19]
	ds_read_b128 v[152:155], v166 offset:34816
	v_mfma_f32_16x16x32_bf16 v[20:23], v[182:185], v[194:197], v[20:23]
	ds_read_b128 v[140:143], v165 offset:4096
	v_mfma_f32_16x16x32_bf16 v[24:27], v[182:185], v[198:201], v[24:27]
	ds_read_b128 v[156:159], v166 offset:36864
	v_mfma_f32_16x16x32_bf16 v[28:31], v[182:185], v[202:205], v[28:31]
	ds_read_b128 v[144:147], v165 offset:6144
	v_mfma_f32_16x16x32_bf16 v[32:35], v[182:185], v[206:209], v[32:35]
	ds_read_b128 v[160:163], v166 offset:38912
	v_mfma_f32_16x16x32_bf16 v[36:39], v[186:189], v[194:197], v[36:39]
	v_mfma_f32_16x16x32_bf16 v[40:43], v[186:189], v[198:201], v[40:43]
	v_mfma_f32_16x16x32_bf16 v[44:47], v[186:189], v[202:205], v[44:47]
	v_mfma_f32_16x16x32_bf16 v[48:51], v[186:189], v[206:209], v[48:51]
	v_mfma_f32_16x16x32_bf16 v[52:55], v[190:193], v[194:197], v[52:55]
	v_mfma_f32_16x16x32_bf16 v[56:59], v[190:193], v[198:201], v[56:59]
	v_mfma_f32_16x16x32_bf16 v[60:63], v[190:193], v[202:205], v[60:63]
	v_mfma_f32_16x16x32_bf16 v[64:67], v[190:193], v[206:209], v[64:67]
	s_waitcnt lgkmcnt(0)
	v_mfma_f32_16x16x32_bf16 v[4:7], v[132:135], v[148:151], v[4:7]
	ds_read_b128 v[178:181], v167
	s_waitcnt vmcnt(8)
	ds_write_b128 v164, v[100:103] offset:16384
	v_mfma_f32_16x16x32_bf16 v[8:11], v[132:135], v[152:155], v[8:11]
	ds_read_b128 v[194:197], v168 offset:32768
	ds_write_b128 v164, v[116:119] offset:49152
	v_mfma_f32_16x16x32_bf16 v[12:15], v[132:135], v[156:159], v[12:15]
	ds_read_b128 v[182:185], v167 offset:2048
	ds_write_b128 v164, v[104:107] offset:20480
	v_mfma_f32_16x16x32_bf16 v[16:19], v[132:135], v[160:163], v[16:19]
	ds_read_b128 v[198:201], v168 offset:34816
	ds_write_b128 v164, v[120:123] offset:53248
	v_mfma_f32_16x16x32_bf16 v[20:23], v[136:139], v[148:151], v[20:23]
	ds_read_b128 v[186:189], v167 offset:4096
	ds_write_b128 v164, v[108:111] offset:24576
	v_mfma_f32_16x16x32_bf16 v[24:27], v[136:139], v[152:155], v[24:27]
	ds_read_b128 v[202:205], v168 offset:36864
	ds_write_b128 v164, v[124:127] offset:57344
	v_mfma_f32_16x16x32_bf16 v[28:31], v[136:139], v[156:159], v[28:31]
	ds_read_b128 v[190:193], v167 offset:6144
	ds_write_b128 v164, v[112:115] offset:28672
	v_mfma_f32_16x16x32_bf16 v[32:35], v[136:139], v[160:163], v[32:35]
	ds_read_b128 v[206:209], v168 offset:38912
	ds_write_b128 v164, v[128:131] offset:61440
	v_mfma_f32_16x16x32_bf16 v[36:39], v[140:143], v[148:151], v[36:39]
	global_load_dwordx4 v[100:103], v169, s[0:1] offset:128
	v_mfma_f32_16x16x32_bf16 v[40:43], v[140:143], v[152:155], v[40:43]
	global_load_dwordx4 v[116:119], v169, s[4:5] offset:128
	v_mfma_f32_16x16x32_bf16 v[44:47], v[140:143], v[156:159], v[44:47]
	global_load_dwordx4 v[104:107], v170, s[0:1] offset:128
	v_mfma_f32_16x16x32_bf16 v[48:51], v[140:143], v[160:163], v[48:51]
	global_load_dwordx4 v[120:123], v170, s[4:5] offset:128
	v_mfma_f32_16x16x32_bf16 v[52:55], v[144:147], v[148:151], v[52:55]
	global_load_dwordx4 v[108:111], v171, s[0:1] offset:128
	v_mfma_f32_16x16x32_bf16 v[56:59], v[144:147], v[152:155], v[56:59]
	global_load_dwordx4 v[124:127], v171, s[4:5] offset:128
	v_mfma_f32_16x16x32_bf16 v[60:63], v[144:147], v[156:159], v[60:63]
	global_load_dwordx4 v[112:115], v172, s[0:1] offset:128
	v_mfma_f32_16x16x32_bf16 v[64:67], v[144:147], v[160:163], v[64:67]
	global_load_dwordx4 v[128:131], v172, s[4:5] offset:128
	s_waitcnt lgkmcnt(0)
	s_barrier
	v_mfma_f32_16x16x32_bf16 v[4:7], v[178:181], v[194:197], v[4:7]
	ds_read_b128 v[132:135], v165 offset:16384
	v_mfma_f32_16x16x32_bf16 v[8:11], v[178:181], v[198:201], v[8:11]
	ds_read_b128 v[148:151], v166 offset:49152
	v_mfma_f32_16x16x32_bf16 v[12:15], v[178:181], v[202:205], v[12:15]
	ds_read_b128 v[136:139], v165 offset:18432
	v_mfma_f32_16x16x32_bf16 v[16:19], v[178:181], v[206:209], v[16:19]
	ds_read_b128 v[152:155], v166 offset:51200
	v_mfma_f32_16x16x32_bf16 v[20:23], v[182:185], v[194:197], v[20:23]
	ds_read_b128 v[140:143], v165 offset:20480
	v_mfma_f32_16x16x32_bf16 v[24:27], v[182:185], v[198:201], v[24:27]
	ds_read_b128 v[156:159], v166 offset:53248
	v_mfma_f32_16x16x32_bf16 v[28:31], v[182:185], v[202:205], v[28:31]
	ds_read_b128 v[144:147], v165 offset:22528
	v_mfma_f32_16x16x32_bf16 v[32:35], v[182:185], v[206:209], v[32:35]
	ds_read_b128 v[160:163], v166 offset:55296
	v_mfma_f32_16x16x32_bf16 v[36:39], v[186:189], v[194:197], v[36:39]
	v_mfma_f32_16x16x32_bf16 v[40:43], v[186:189], v[198:201], v[40:43]
	v_mfma_f32_16x16x32_bf16 v[44:47], v[186:189], v[202:205], v[44:47]
	v_mfma_f32_16x16x32_bf16 v[48:51], v[186:189], v[206:209], v[48:51]
	v_mfma_f32_16x16x32_bf16 v[52:55], v[190:193], v[194:197], v[52:55]
	v_mfma_f32_16x16x32_bf16 v[56:59], v[190:193], v[198:201], v[56:59]
	v_mfma_f32_16x16x32_bf16 v[60:63], v[190:193], v[202:205], v[60:63]
	v_mfma_f32_16x16x32_bf16 v[64:67], v[190:193], v[206:209], v[64:67]
	s_waitcnt lgkmcnt(0)
	v_mfma_f32_16x16x32_bf16 v[4:7], v[132:135], v[148:151], v[4:7]
	ds_read_b128 v[178:181], v167 offset:16384
	v_mfma_f32_16x16x32_bf16 v[8:11], v[132:135], v[152:155], v[8:11]
	ds_read_b128 v[194:197], v168 offset:49152
	v_mfma_f32_16x16x32_bf16 v[12:15], v[132:135], v[156:159], v[12:15]
	ds_read_b128 v[182:185], v167 offset:18432
	v_mfma_f32_16x16x32_bf16 v[16:19], v[132:135], v[160:163], v[16:19]
	ds_read_b128 v[198:201], v168 offset:51200
	v_mfma_f32_16x16x32_bf16 v[20:23], v[136:139], v[148:151], v[20:23]
	ds_read_b128 v[186:189], v167 offset:20480
	v_mfma_f32_16x16x32_bf16 v[24:27], v[136:139], v[152:155], v[24:27]
	ds_read_b128 v[202:205], v168 offset:53248
	v_mfma_f32_16x16x32_bf16 v[28:31], v[136:139], v[156:159], v[28:31]
	ds_read_b128 v[190:193], v167 offset:22528
	v_mfma_f32_16x16x32_bf16 v[32:35], v[136:139], v[160:163], v[32:35]
	ds_read_b128 v[206:209], v168 offset:55296
	v_mfma_f32_16x16x32_bf16 v[36:39], v[140:143], v[148:151], v[36:39]
	v_mfma_f32_16x16x32_bf16 v[40:43], v[140:143], v[152:155], v[40:43]
	v_mfma_f32_16x16x32_bf16 v[44:47], v[140:143], v[156:159], v[44:47]
	v_mfma_f32_16x16x32_bf16 v[48:51], v[140:143], v[160:163], v[48:51]
	v_mfma_f32_16x16x32_bf16 v[52:55], v[144:147], v[148:151], v[52:55]
	v_mfma_f32_16x16x32_bf16 v[56:59], v[144:147], v[152:155], v[56:59]
	v_mfma_f32_16x16x32_bf16 v[60:63], v[144:147], v[156:159], v[60:63]
	v_mfma_f32_16x16x32_bf16 v[64:67], v[144:147], v[160:163], v[64:67]
	s_waitcnt lgkmcnt(0)
	s_barrier
	v_mfma_f32_16x16x32_bf16 v[4:7], v[178:181], v[194:197], v[4:7]
	v_mfma_f32_16x16x32_bf16 v[8:11], v[178:181], v[198:201], v[8:11]
	v_mfma_f32_16x16x32_bf16 v[12:15], v[178:181], v[202:205], v[12:15]
	v_mfma_f32_16x16x32_bf16 v[16:19], v[178:181], v[206:209], v[16:19]
	v_mfma_f32_16x16x32_bf16 v[20:23], v[182:185], v[194:197], v[20:23]
	v_mfma_f32_16x16x32_bf16 v[24:27], v[182:185], v[198:201], v[24:27]
	v_mfma_f32_16x16x32_bf16 v[28:31], v[182:185], v[202:205], v[28:31]
	v_mfma_f32_16x16x32_bf16 v[32:35], v[182:185], v[206:209], v[32:35]
	v_mfma_f32_16x16x32_bf16 v[36:39], v[186:189], v[194:197], v[36:39]
	v_mfma_f32_16x16x32_bf16 v[40:43], v[186:189], v[198:201], v[40:43]
	v_mfma_f32_16x16x32_bf16 v[44:47], v[186:189], v[202:205], v[44:47]
	v_mfma_f32_16x16x32_bf16 v[48:51], v[186:189], v[206:209], v[48:51]
	v_mfma_f32_16x16x32_bf16 v[52:55], v[190:193], v[194:197], v[52:55]
	v_mfma_f32_16x16x32_bf16 v[56:59], v[190:193], v[198:201], v[56:59]
	v_mfma_f32_16x16x32_bf16 v[60:63], v[190:193], v[202:205], v[60:63]
	v_mfma_f32_16x16x32_bf16 v[64:67], v[190:193], v[206:209], v[64:67]
	s_nop 7
	v_cvt_pk_bf16_f32 v210, v4, v5
	v_cvt_pk_bf16_f32 v211, v6, v7
	ds_write_b64 v173, v[210:211]
	v_cvt_pk_bf16_f32 v212, v20, v21
	v_cvt_pk_bf16_f32 v213, v22, v23
	ds_write_b64 v173, v[212:213] offset:32
	v_cvt_pk_bf16_f32 v214, v36, v37
	v_cvt_pk_bf16_f32 v215, v38, v39
	ds_write_b64 v173, v[214:215] offset:64
	v_cvt_pk_bf16_f32 v216, v52, v53
	v_cvt_pk_bf16_f32 v217, v54, v55
	ds_write_b64 v173, v[216:217] offset:96
	v_cvt_pk_bf16_f32 v210, v8, v9
	v_cvt_pk_bf16_f32 v211, v10, v11
	ds_write_b64 v173, v[210:211] offset:4352
	v_cvt_pk_bf16_f32 v212, v24, v25
	v_cvt_pk_bf16_f32 v213, v26, v27
	ds_write_b64 v173, v[212:213] offset:4384
	v_cvt_pk_bf16_f32 v214, v40, v41
	v_cvt_pk_bf16_f32 v215, v42, v43
	ds_write_b64 v173, v[214:215] offset:4416
	v_cvt_pk_bf16_f32 v216, v56, v57
	v_cvt_pk_bf16_f32 v217, v58, v59
	ds_write_b64 v173, v[216:217] offset:4448
	v_cvt_pk_bf16_f32 v210, v12, v13
	v_cvt_pk_bf16_f32 v211, v14, v15
	ds_write_b64 v173, v[210:211] offset:8704
	v_cvt_pk_bf16_f32 v212, v28, v29
	v_cvt_pk_bf16_f32 v213, v30, v31
	ds_write_b64 v173, v[212:213] offset:8736
	v_cvt_pk_bf16_f32 v214, v44, v45
	v_cvt_pk_bf16_f32 v215, v46, v47
	ds_write_b64 v173, v[214:215] offset:8768
	v_cvt_pk_bf16_f32 v216, v60, v61
	v_cvt_pk_bf16_f32 v217, v62, v63
	ds_write_b64 v173, v[216:217] offset:8800
	v_cvt_pk_bf16_f32 v210, v16, v17
	v_cvt_pk_bf16_f32 v211, v18, v19
	ds_write_b64 v173, v[210:211] offset:13056
	v_cvt_pk_bf16_f32 v212, v32, v33
	v_cvt_pk_bf16_f32 v213, v34, v35
	ds_write_b64 v173, v[212:213] offset:13088
	v_cvt_pk_bf16_f32 v214, v48, v49
	v_cvt_pk_bf16_f32 v215, v50, v51
	ds_write_b64 v173, v[214:215] offset:13120
	v_cvt_pk_bf16_f32 v216, v64, v65
	v_cvt_pk_bf16_f32 v217, v66, v67
	ds_write_b64 v173, v[216:217] offset:13152
	s_waitcnt lgkmcnt(0)
	s_barrier
	ds_read_b128 v[132:135], v174
	ds_read_b128 v[136:139], v174 offset:4352
	ds_read_b128 v[140:143], v174 offset:8704
	ds_read_b128 v[144:147], v174 offset:13056
	ds_read_b128 v[148:151], v174 offset:17408
	ds_read_b128 v[152:155], v174 offset:21760
	ds_read_b128 v[156:159], v174 offset:26112
	ds_read_b128 v[160:163], v174 offset:30464
	s_waitcnt lgkmcnt(7)
	global_store_dwordx4 v175, v[132:135], s[6:7]
	s_add_u32 s6, s6, 0x8000
	s_addc_u32 s7, s7, 0
	s_waitcnt lgkmcnt(6)
	global_store_dwordx4 v175, v[136:139], s[6:7]
	s_add_u32 s6, s6, 0x8000
	s_addc_u32 s7, s7, 0
	s_waitcnt lgkmcnt(5)
	global_store_dwordx4 v175, v[140:143], s[6:7]
	s_add_u32 s6, s6, 0x8000
	s_addc_u32 s7, s7, 0
	s_waitcnt lgkmcnt(4)
	global_store_dwordx4 v175, v[144:147], s[6:7]
	s_add_u32 s6, s6, 0x8000
	s_addc_u32 s7, s7, 0
	s_waitcnt lgkmcnt(3)
	global_store_dwordx4 v175, v[148:151], s[6:7]
	s_add_u32 s6, s6, 0x8000
	s_addc_u32 s7, s7, 0
	s_waitcnt lgkmcnt(2)
	global_store_dwordx4 v175, v[152:155], s[6:7]
	s_add_u32 s6, s6, 0x8000
	s_addc_u32 s7, s7, 0
	s_waitcnt lgkmcnt(1)
	global_store_dwordx4 v175, v[156:159], s[6:7]
	s_add_u32 s6, s6, 0x8000
	s_addc_u32 s7, s7, 0
	s_waitcnt lgkmcnt(0)
	global_store_dwordx4 v175, v[160:163], s[6:7]
	s_barrier
	s_add_i32 s10, s10, s13
	s_cmp_lt_u32 s10, 272
	s_cbranch_scc1 .Lg1_again
.Lg1_done:
.LBB0_1121:
	s_getreg_b32 s4, hwreg(HW_REG_XCC_ID, 0, 4)
	s_waitcnt vmcnt(0)
	s_barrier
	s_mov_b64 s[0:1], exec
	v_readlane_b32 s6, v253, 13
	v_readlane_b32 s7, v253, 14
	s_and_b64 s[6:7], s[0:1], s[6:7]
	s_movk_i32 s17, 0xc00
	s_mov_b64 exec, s[6:7]
	s_cbranch_execnz .LBB0_1122
	s_getpc_b64 s[98:99]
